# attention inner loop regenerated by hand: MFMAs evenly interleaved with softmax VALU, exp in place, SGPR-based prefetch, deferred PV pair across barrier
# speedup vs baseline: 1.0327x; 1.0244x over previous
.LBB0_737:
	s_or_b64 exec, exec, s[4:5]
	global_load_dwordx4 v[132:135], v[12:13], off offset:128
	v_add_u32_e32 v0, v178, v148
	s_waitcnt vmcnt(1)
	ds_write_b128 v0, v[128:131] offset:22016
	s_and_saveexec_b64 s[4:5], s[2:3]
	ds_write_b128 v186, v[124:127] offset:22144
	s_or_b64 exec, exec, s[4:5]
	s_waitcnt vmcnt(0)
	ds_write2_b64 v149, v[132:133], v[134:135] offset1:1
	s_waitcnt lgkmcnt(0)
	s_barrier
	ds_read_b128 v[0:3], v185
	ds_read_b128 v[4:7], v185 offset:32
	s_waitcnt lgkmcnt(1)
	v_mfma_f32_32x32x16_bf16 v[48:63], v[0:3], v[100:103], 0
	s_mov_b32 s4, 0
	s_mov_b32 s5, s4
	s_mov_b32 s6, s4
	s_mov_b32 s7, s4
	s_mov_b32 s8, s4
	s_mov_b32 s9, s4
	s_mov_b32 s10, s4
	s_waitcnt lgkmcnt(0)
	v_mfma_f32_32x32x16_bf16 v[48:63], v[4:7], v[104:107], v[48:63]
	ds_read_b128 v[0:3], v185 offset:64
	ds_read_b128 v[4:7], v185 offset:96
	s_mov_b32 s11, s4
	s_mov_b32 s12, s4
	s_mov_b32 s13, s4
	s_mov_b32 s14, s4
	s_mov_b32 s15, s4
	s_mov_b32 s16, s4
	s_waitcnt lgkmcnt(1)
	v_mfma_f32_32x32x16_bf16 v[48:63], v[0:3], v[108:111], v[48:63]
	s_mov_b32 s17, s4
	s_mov_b32 s18, s4
	s_mov_b32 s19, s4
	s_waitcnt lgkmcnt(0)
	v_mfma_f32_32x32x16_bf16 v[48:63], v[4:7], v[112:115], v[48:63]
	ds_read_b128 v[0:3], v185 offset:128
	ds_read_b128 v[4:7], v185 offset:160
	s_waitcnt lgkmcnt(1)
	v_mfma_f32_32x32x16_bf16 v[48:63], v[0:3], v[116:119], v[48:63]
	s_waitcnt lgkmcnt(0)
	v_mfma_f32_32x32x16_bf16 v[48:63], v[4:7], v[120:123], v[48:63]
	ds_read_b128 v[0:3], v185 offset:6656
	ds_read_b128 v[4:7], v185 offset:6688
	s_waitcnt lgkmcnt(1)
	v_mfma_f32_32x32x16_bf16 v[32:47], v[0:3], v[100:103], 0
	s_waitcnt lgkmcnt(0)
	v_mfma_f32_32x32x16_bf16 v[32:47], v[4:7], v[104:107], v[32:47]
	ds_read_b128 v[0:3], v185 offset:6720
	ds_read_b128 v[4:7], v185 offset:6752
	ds_read_b128 v[16:19], v185 offset:6816
	s_waitcnt lgkmcnt(2)
	v_mfma_f32_32x32x16_bf16 v[32:47], v[0:3], v[108:111], v[32:47]
	ds_read_b128 v[0:3], v185 offset:6784
	s_waitcnt lgkmcnt(2)
	v_mfma_f32_32x32x16_bf16 v[32:47], v[4:7], v[112:115], v[32:47]
	s_waitcnt lgkmcnt(0)
	v_mfma_f32_32x32x16_bf16 v[32:47], v[0:3], v[116:119], v[32:47]
	v_mov_b64_e32 v[0:1], s[4:5]
	v_mov_b64_e32 v[2:3], s[6:7]
	v_mov_b64_e32 v[4:5], s[8:9]
	v_mov_b64_e32 v[6:7], s[10:11]
	v_mov_b64_e32 v[8:9], s[12:13]
	v_mov_b64_e32 v[10:11], s[14:15]
	v_mov_b64_e32 v[12:13], s[16:17]
	v_mfma_f32_32x32x16_bf16 v[32:47], v[16:19], v[120:123], v[32:47]
	v_mov_b64_e32 v[14:15], s[18:19]
	s_nop 15
	s_nop 15
	s_nop 15
	v_mov_b64_e32 v[30:31], v[14:15]
	v_lshl_add_u64 v[98:99], v[152:153], 0, s[34:35]
	v_lshl_add_u64 v[168:169], v[146:147], 0, s[0:1]
	v_lshl_add_u64 v[170:171], v[154:155], 0, s[0:1]
	v_mov_b32_e32 v157, 0
	v_mov_b64_e32 v[28:29], v[12:13]
	v_mov_b64_e32 v[26:27], v[10:11]
	v_mov_b64_e32 v[24:25], v[8:9]
	v_mov_b64_e32 v[22:23], v[6:7]
	v_mov_b64_e32 v[20:21], v[4:5]
	v_mov_b64_e32 v[18:19], v[2:3]
	v_mov_b64_e32 v[16:17], v[0:1]
	v_mov_b32_e32 v96, 0
	v_mov_b32_e32 v228, 0x80000000
	v_mov_b32_e32 v229, v228
	v_mov_b32_e32 v230, v228
	v_mov_b32_e32 v231, v228
	v_mov_b32_e32 v232, v228
	v_mov_b32_e32 v233, v228
	v_mov_b32_e32 v234, v228
	v_mov_b32_e32 v235, v228
	v_mov_b32_e32 v236, v228
	v_mov_b32_e32 v237, v228
	v_mov_b32_e32 v238, v228
	v_mov_b32_e32 v239, v228
	v_mov_b32_e32 v240, v228
	v_mov_b32_e32 v241, v228
	v_mov_b32_e32 v242, v228
	v_mov_b32_e32 v243, v228
	s_add_u32 s48, s37, s0
	s_addc_u32 s49, s38, s1
	s_add_u32 s48, s48, 0x4000
	s_addc_u32 s49, s49, 0
	s_add_u32 s50, s39, s34
	s_addc_u32 s51, s40, s35
	s_add_u32 s50, s50, 0x2000
	s_addc_u32 s51, s51, 0
	s_add_u32 s60, s54, 0x1cd00000
	s_addc_u32 s61, s55, 0
	s_add_u32 s60, s60, s0
	s_addc_u32 s61, s61, s1
	s_add_u32 s60, s60, 0x100
	s_addc_u32 s61, s61, 0
	s_mov_b32 s44, 0
	s_movk_i32 s45, 0x5600
	s_mov_b32 s46, 0xac00
	v_add_u32_e32 v168, v141, v148
	v_add_u32_e32 v169, v174, v175
	v_add3_u32 v170, v176, v148, s41
	v_add3_u32 v171, v182, v136, s41
	v_add3_u32 v172, v183, v136, s41
	v_add_u32_e32 v173, v180, v179
	v_add_u32_e32 v98, v181, v179
	v_and_b32_e32 v99, 0xfff, v152
	v_mov_b32_e32 v212, 0
	v_mov_b32_e32 v213, 0
	v_mov_b32_e32 v214, 0
	v_mov_b32_e32 v215, 0
	v_mov_b32_e32 v216, 0
	v_mov_b32_e32 v217, 0
	v_mov_b32_e32 v218, 0
	v_mov_b32_e32 v219, 0
	v_mov_b32_e32 v220, 0
	v_mov_b32_e32 v221, 0
	v_mov_b32_e32 v222, 0
	v_mov_b32_e32 v223, 0
	global_load_dwordx4 v[128:131], v154, s[48:49]
	global_load_dwordx4 v[124:127], v99, s[50:51]
	global_load_dwordx4 v[132:135], v146, s[60:61]
.LBB0_740:
	s_cmp_eq_u32 s4, 0
	s_cselect_b64 s[76:77], -1, 0
	v_add_u32_e32 v227, s45, v173
	v_add_u32_e32 v245, s45, v98
	ds_read_b128 v[188:191], v227
	ds_read_b128 v[192:195], v245
	ds_read_b128 v[196:199], v227 offset:32
	ds_read_b128 v[200:203], v245 offset:32
	v_mfma_f32_32x32x16_bf16 v[0:15], v[212:215], v[220:223], v[0:15]
	v_add_u32_e32 v246, s44, v171
	v_add_u32_e32 v247, s44, v172
	v_mov_b32_e32 v161, 0
	v_mfma_f32_32x32x16_bf16 v[16:31], v[216:219], v[220:223], v[16:31]
	s_waitcnt lgkmcnt(3)
	v_mfma_f32_32x32x16_bf16 v[80:95], v[188:191], v[100:103], v[228:243]
	ds_read_b128 v[188:191], v227 offset:64
	v_max3_f32 v224, v48, v49, v50
	v_max3_f32 v224, v224, v51, v52
	v_max3_f32 v224, v224, v53, v54
	v_max3_f32 v225, v33, v34, v35
	v_max3_f32 v225, v225, v36, v37
	s_waitcnt lgkmcnt(3)
	v_mfma_f32_32x32x16_bf16 v[64:79], v[192:195], v[100:103], v[228:243]
	ds_read_b128 v[192:195], v245 offset:64
	v_max3_f32 v224, v224, v55, v56
	v_max3_f32 v224, v224, v57, v58
	v_max3_f32 v224, v224, v59, v60
	v_max3_f32 v225, v225, v38, v39
	v_max3_f32 v225, v225, v40, v41
	s_waitcnt lgkmcnt(3)
	v_mfma_f32_32x32x16_bf16 v[80:95], v[196:199], v[104:107], v[80:95]
	ds_read_b128 v[196:199], v227 offset:96
	ds_read2_b64 v[204:207], v246 offset0:0 offset1:2
	ds_read2_b64 v[208:211], v247 offset0:0 offset1:2
	v_max3_f32 v224, v224, v61, v62
	v_max3_f32 v224, v224, v63, v32
	v_max3_f32 v225, v225, v42, v43
	v_max3_f32 v225, v225, v44, v45
	v_max3_f32 v225, v225, v46, v47
	s_waitcnt lgkmcnt(5)
	v_mfma_f32_32x32x16_bf16 v[64:79], v[200:203], v[104:107], v[64:79]
	ds_read_b128 v[200:203], v245 offset:96
	v_max_f32_e32 v224, v224, v225
	v_mov_b32_e32 v226, v224
	v_add_u32_e32 v159, s46, v168
	s_nop 0
	v_permlane32_swap_b32_e32 v224, v226
	v_max_f32_e32 v224, v224, v226
	v_cmp_lt_f32_e32 vcc, s42, v224
	s_or_b64 vcc, s[76:77], vcc
	s_cbranch_vccz .Lattn_e_norare
	s_nop 15
	v_max_f32_e32 v225, v224, v224
	v_max_f32_e32 v225, 0, v225
	v_cndmask_b32_e64 v225, v225, v224, s[76:77]
	v_exp_f32_e64 v226, -v225
	v_add_f32_e32 v96, v96, v225
	v_cndmask_b32_e64 v226, v226, 1.0, s[76:77]
	v_mul_f32_e32 v157, v157, v226
	v_sub_f32_e32 v48, v48, v225
	v_sub_f32_e32 v49, v49, v225
	v_sub_f32_e32 v50, v50, v225
	v_sub_f32_e32 v51, v51, v225
	v_sub_f32_e32 v52, v52, v225
	v_sub_f32_e32 v53, v53, v225
	v_sub_f32_e32 v54, v54, v225
	v_sub_f32_e32 v55, v55, v225
	v_sub_f32_e32 v56, v56, v225
	v_sub_f32_e32 v57, v57, v225
	v_sub_f32_e32 v58, v58, v225
	v_sub_f32_e32 v59, v59, v225
	v_sub_f32_e32 v60, v60, v225
	v_sub_f32_e32 v61, v61, v225
	v_sub_f32_e32 v62, v62, v225
	v_sub_f32_e32 v63, v63, v225
	v_sub_f32_e32 v32, v32, v225
	v_sub_f32_e32 v33, v33, v225
	v_sub_f32_e32 v34, v34, v225
	v_sub_f32_e32 v35, v35, v225
	v_sub_f32_e32 v36, v36, v225
	v_sub_f32_e32 v37, v37, v225
	v_sub_f32_e32 v38, v38, v225
	v_sub_f32_e32 v39, v39, v225
	v_sub_f32_e32 v40, v40, v225
	v_sub_f32_e32 v41, v41, v225
	v_sub_f32_e32 v42, v42, v225
	v_sub_f32_e32 v43, v43, v225
	v_sub_f32_e32 v44, v44, v225
	v_sub_f32_e32 v45, v45, v225
	v_sub_f32_e32 v46, v46, v225
	v_sub_f32_e32 v47, v47, v225
	v_sub_f32_e32 v80, v80, v225
	v_sub_f32_e32 v81, v81, v225
	v_sub_f32_e32 v82, v82, v225
	v_sub_f32_e32 v83, v83, v225
	v_sub_f32_e32 v84, v84, v225
	v_sub_f32_e32 v85, v85, v225
	v_sub_f32_e32 v86, v86, v225
	v_sub_f32_e32 v87, v87, v225
	v_sub_f32_e32 v88, v88, v225
	v_sub_f32_e32 v89, v89, v225
	v_sub_f32_e32 v90, v90, v225
	v_sub_f32_e32 v91, v91, v225
	v_sub_f32_e32 v92, v92, v225
	v_sub_f32_e32 v93, v93, v225
	v_sub_f32_e32 v94, v94, v225
	v_sub_f32_e32 v95, v95, v225
	v_sub_f32_e32 v64, v64, v225
	v_sub_f32_e32 v65, v65, v225
	v_sub_f32_e32 v66, v66, v225
	v_sub_f32_e32 v67, v67, v225
	v_sub_f32_e32 v68, v68, v225
	v_sub_f32_e32 v69, v69, v225
	v_sub_f32_e32 v70, v70, v225
	v_sub_f32_e32 v71, v71, v225
	v_sub_f32_e32 v72, v72, v225
	v_sub_f32_e32 v73, v73, v225
	v_sub_f32_e32 v74, v74, v225
	v_sub_f32_e32 v75, v75, v225
	v_sub_f32_e32 v76, v76, v225
	v_sub_f32_e32 v77, v77, v225
	v_sub_f32_e32 v78, v78, v225
	v_sub_f32_e32 v79, v79, v225
	v_pk_mul_f32 v[0:1], v[0:1], v[226:227] op_sel_hi:[1,0]
	v_pk_mul_f32 v[2:3], v[2:3], v[226:227] op_sel_hi:[1,0]
	v_pk_mul_f32 v[4:5], v[4:5], v[226:227] op_sel_hi:[1,0]
	v_pk_mul_f32 v[6:7], v[6:7], v[226:227] op_sel_hi:[1,0]
	v_pk_mul_f32 v[8:9], v[8:9], v[226:227] op_sel_hi:[1,0]
	v_pk_mul_f32 v[10:11], v[10:11], v[226:227] op_sel_hi:[1,0]
	v_pk_mul_f32 v[12:13], v[12:13], v[226:227] op_sel_hi:[1,0]
	v_pk_mul_f32 v[14:15], v[14:15], v[226:227] op_sel_hi:[1,0]
	v_pk_mul_f32 v[16:17], v[16:17], v[226:227] op_sel_hi:[1,0]
	v_pk_mul_f32 v[18:19], v[18:19], v[226:227] op_sel_hi:[1,0]
	v_pk_mul_f32 v[20:21], v[20:21], v[226:227] op_sel_hi:[1,0]
	v_pk_mul_f32 v[22:23], v[22:23], v[226:227] op_sel_hi:[1,0]
	v_pk_mul_f32 v[24:25], v[24:25], v[226:227] op_sel_hi:[1,0]
	v_pk_mul_f32 v[26:27], v[26:27], v[226:227] op_sel_hi:[1,0]
	v_pk_mul_f32 v[28:29], v[28:29], v[226:227] op_sel_hi:[1,0]
	v_pk_mul_f32 v[30:31], v[30:31], v[226:227] op_sel_hi:[1,0]
	v_xor_b32_e32 v228, 0x80000000, v96
	v_mov_b32_e32 v229, v228
	v_mov_b32_e32 v230, v228
	v_mov_b32_e32 v231, v228
	v_mov_b32_e32 v232, v228
	v_mov_b32_e32 v233, v228
	v_mov_b32_e32 v234, v228
	v_mov_b32_e32 v235, v228
	v_mov_b32_e32 v236, v228
	v_mov_b32_e32 v237, v228
	v_mov_b32_e32 v238, v228
	v_mov_b32_e32 v239, v228
	v_mov_b32_e32 v240, v228
	v_mov_b32_e32 v241, v228
	v_mov_b32_e32 v242, v228
	v_mov_b32_e32 v243, v228
.Lattn_e_norare:
	s_waitcnt lgkmcnt(5)
	v_mfma_f32_32x32x16_bf16 v[80:95], v[188:191], v[108:111], v[80:95]
	ds_read_b128 v[188:191], v227 offset:128
	v_exp_f32_e32 v48, v48
	v_exp_f32_e32 v49, v49
	v_exp_f32_e32 v50, v50
	v_exp_f32_e32 v51, v51
	s_waitcnt lgkmcnt(5)
	v_mfma_f32_32x32x16_bf16 v[64:79], v[192:195], v[108:111], v[64:79]
	v_exp_f32_e32 v52, v52
	v_exp_f32_e32 v53, v53
	v_exp_f32_e32 v54, v54
	v_exp_f32_e32 v55, v55
	s_waitcnt lgkmcnt(4)
	v_mfma_f32_32x32x16_bf16 v[80:95], v[196:199], v[112:115], v[80:95]
	ds_read2_b64 v[212:215], v246 offset0:4 offset1:6
	ds_read2_b64 v[216:219], v247 offset0:4 offset1:6
	v_cvt_pk_bf16_f32 v220, v48, v49
	v_cvt_pk_bf16_f32 v221, v50, v51
	v_cvt_pk_bf16_f32 v222, v52, v53
	v_cvt_pk_bf16_f32 v223, v54, v55
	v_add_f32_e32 v161, v161, v48
	v_add_f32_e32 v161, v161, v49
	v_add_f32_e32 v161, v161, v50
	v_add_f32_e32 v161, v161, v51
	s_waitcnt lgkmcnt(5)
	v_mfma_f32_32x32x16_bf16 v[0:15], v[204:207], v[220:223], v[0:15]
	v_add_f32_e32 v161, v161, v52
	v_add_f32_e32 v161, v161, v53
	v_add_f32_e32 v161, v161, v54
	v_add_f32_e32 v161, v161, v55
	v_exp_f32_e32 v56, v56
	v_exp_f32_e32 v57, v57
	s_waitcnt lgkmcnt(4)
	v_mfma_f32_32x32x16_bf16 v[16:31], v[208:211], v[220:223], v[16:31]
	ds_read_b128 v[192:195], v245 offset:128
	v_exp_f32_e32 v58, v58
	v_exp_f32_e32 v59, v59
	v_exp_f32_e32 v60, v60
	v_exp_f32_e32 v61, v61
	s_waitcnt lgkmcnt(4)
	v_mfma_f32_32x32x16_bf16 v[64:79], v[200:203], v[112:115], v[64:79]
	ds_read_b128 v[196:199], v227 offset:160
	v_exp_f32_e32 v62, v62
	v_exp_f32_e32 v63, v63
	v_cvt_pk_bf16_f32 v220, v56, v57
	v_cvt_pk_bf16_f32 v221, v58, v59
	v_cvt_pk_bf16_f32 v222, v60, v61
	v_cvt_pk_bf16_f32 v223, v62, v63
	s_waitcnt lgkmcnt(4)
	v_mfma_f32_32x32x16_bf16 v[80:95], v[188:191], v[116:119], v[80:95]
	ds_read2_b64 v[204:207], v246 offset0:8 offset1:10
	ds_read2_b64 v[208:211], v247 offset0:8 offset1:10
	v_add_f32_e32 v161, v161, v56
	v_add_f32_e32 v161, v161, v57
	v_add_f32_e32 v161, v161, v58
	v_add_f32_e32 v161, v161, v59
	v_add_f32_e32 v161, v161, v60
	v_add_f32_e32 v161, v161, v61
	v_add_f32_e32 v161, v161, v62
	v_add_f32_e32 v161, v161, v63
	s_waitcnt lgkmcnt(5)
	v_mfma_f32_32x32x16_bf16 v[0:15], v[212:215], v[220:223], v[0:15]
	v_exp_f32_e32 v32, v32
	v_exp_f32_e32 v33, v33
	v_exp_f32_e32 v34, v34
	v_exp_f32_e32 v35, v35
	s_waitcnt lgkmcnt(4)
	v_mfma_f32_32x32x16_bf16 v[16:31], v[216:219], v[220:223], v[16:31]
	ds_read_b128 v[200:203], v245 offset:160
	s_waitcnt vmcnt(0)
	ds_write_b128 v159, v[128:131]
	v_add_u32_e32 v159, s46, v169
	ds_write_b128 v159, v[124:127] offset:128
	v_add_u32_e32 v159, s46, v170
	ds_write2_b64 v159, v[132:133], v[134:135] offset1:1
	v_exp_f32_e32 v36, v36
	v_exp_f32_e32 v37, v37
	v_exp_f32_e32 v38, v38
	v_exp_f32_e32 v39, v39
	s_waitcnt lgkmcnt(7)
	v_mfma_f32_32x32x16_bf16 v[64:79], v[192:195], v[116:119], v[64:79]
	ds_read2_b64 v[212:215], v246 offset0:12 offset1:14
	ds_read2_b64 v[216:219], v247 offset0:12 offset1:14
	s_cmpk_gt_u32 s4, 0x40
	s_cbranch_scc1 .Lattn_e_nopf
	s_add_u32 s48, s48, 0x2000
	s_addc_u32 s49, s49, 0
	s_add_u32 s50, s50, 0x1000
	s_addc_u32 s51, s51, 0
	s_add_u32 s60, s60, 0x80
	s_addc_u32 s61, s61, 0
	global_load_dwordx4 v[128:131], v154, s[48:49]
	global_load_dwordx4 v[124:127], v99, s[50:51]
	global_load_dwordx4 v[132:135], v146, s[60:61]
.Lattn_e_nopf:
	v_cvt_pk_bf16_f32 v220, v32, v33
	v_cvt_pk_bf16_f32 v221, v34, v35
	v_cvt_pk_bf16_f32 v222, v36, v37
	v_cvt_pk_bf16_f32 v223, v38, v39
	v_add_f32_e32 v161, v161, v32
	v_add_f32_e32 v161, v161, v33
	v_add_f32_e32 v161, v161, v34
	v_add_f32_e32 v161, v161, v35
	s_waitcnt lgkmcnt(8)
	v_mfma_f32_32x32x16_bf16 v[80:95], v[196:199], v[120:123], v[80:95]
	v_add_f32_e32 v161, v161, v36
	v_add_f32_e32 v161, v161, v37
	v_add_f32_e32 v161, v161, v38
	v_add_f32_e32 v161, v161, v39
	v_exp_f32_e32 v40, v40
	v_exp_f32_e32 v41, v41
	s_waitcnt lgkmcnt(7)
	v_mfma_f32_32x32x16_bf16 v[0:15], v[204:207], v[220:223], v[0:15]
	v_exp_f32_e32 v42, v42
	v_exp_f32_e32 v43, v43
	v_exp_f32_e32 v44, v44
	v_exp_f32_e32 v45, v45
	s_waitcnt lgkmcnt(6)
	v_mfma_f32_32x32x16_bf16 v[16:31], v[208:211], v[220:223], v[16:31]
	v_exp_f32_e32 v46, v46
	v_exp_f32_e32 v47, v47
	v_cvt_pk_bf16_f32 v220, v40, v41
	v_cvt_pk_bf16_f32 v221, v42, v43
	v_cvt_pk_bf16_f32 v222, v44, v45
	v_cvt_pk_bf16_f32 v223, v46, v47
	s_waitcnt lgkmcnt(5)
	v_mfma_f32_32x32x16_bf16 v[64:79], v[200:203], v[120:123], v[64:79]
	v_add_f32_e32 v161, v161, v40
	v_add_f32_e32 v161, v161, v41
	v_add_f32_e32 v161, v161, v42
	v_add_f32_e32 v161, v161, v43
	v_add_f32_e32 v161, v161, v44
	v_add_f32_e32 v161, v161, v45
	v_add_f32_e32 v161, v161, v46
	v_add_f32_e32 v161, v161, v47
	s_mov_b32 s47, s44
	s_mov_b32 s44, s45
	s_mov_b32 s45, s46
	s_mov_b32 s46, s47
	v_add_f32_e32 v157, v157, v161
	s_waitcnt lgkmcnt(0)
	s_barrier
	v_add_u32_e32 v227, s45, v173
	v_add_u32_e32 v245, s45, v98
	ds_read_b128 v[188:191], v227
	ds_read_b128 v[192:195], v245
	ds_read_b128 v[196:199], v227 offset:32
	ds_read_b128 v[200:203], v245 offset:32
	v_mfma_f32_32x32x16_bf16 v[0:15], v[212:215], v[220:223], v[0:15]
	v_add_u32_e32 v246, s44, v171
	v_add_u32_e32 v247, s44, v172
	v_mov_b32_e32 v161, 0
	v_mfma_f32_32x32x16_bf16 v[16:31], v[216:219], v[220:223], v[16:31]
	s_waitcnt lgkmcnt(3)
	v_mfma_f32_32x32x16_bf16 v[48:63], v[188:191], v[100:103], v[228:243]
	ds_read_b128 v[188:191], v227 offset:64
	v_max3_f32 v224, v80, v81, v82
	v_max3_f32 v224, v224, v83, v84
	v_max3_f32 v224, v224, v85, v86
	v_max3_f32 v225, v65, v66, v67
	v_max3_f32 v225, v225, v68, v69
	s_waitcnt lgkmcnt(3)
	v_mfma_f32_32x32x16_bf16 v[32:47], v[192:195], v[100:103], v[228:243]
	ds_read_b128 v[192:195], v245 offset:64
	v_max3_f32 v224, v224, v87, v88
	v_max3_f32 v224, v224, v89, v90
	v_max3_f32 v224, v224, v91, v92
	v_max3_f32 v225, v225, v70, v71
	v_max3_f32 v225, v225, v72, v73
	s_waitcnt lgkmcnt(3)
	v_mfma_f32_32x32x16_bf16 v[48:63], v[196:199], v[104:107], v[48:63]
	ds_read_b128 v[196:199], v227 offset:96
	ds_read2_b64 v[204:207], v246 offset0:0 offset1:2
	ds_read2_b64 v[208:211], v247 offset0:0 offset1:2
	v_max3_f32 v224, v224, v93, v94
	v_max3_f32 v224, v224, v95, v64
	v_max3_f32 v225, v225, v74, v75
	v_max3_f32 v225, v225, v76, v77
	v_max3_f32 v225, v225, v78, v79
	s_waitcnt lgkmcnt(5)
	v_mfma_f32_32x32x16_bf16 v[32:47], v[200:203], v[104:107], v[32:47]
	ds_read_b128 v[200:203], v245 offset:96
	v_max_f32_e32 v224, v224, v225
	v_mov_b32_e32 v226, v224
	v_add_u32_e32 v159, s46, v168
	s_nop 0
	v_permlane32_swap_b32_e32 v224, v226
	v_max_f32_e32 v224, v224, v226
	v_cmp_lt_f32_e32 vcc, s42, v224
	s_cbranch_vccz .Lattn_o_norare
	s_nop 15
	v_max_f32_e32 v225, v224, v224
	v_max_f32_e32 v225, 0, v225
	v_exp_f32_e64 v226, -v225
	v_add_f32_e32 v96, v96, v225
	s_nop 0
	v_mul_f32_e32 v157, v157, v226
	v_sub_f32_e32 v80, v80, v225
	v_sub_f32_e32 v81, v81, v225
	v_sub_f32_e32 v82, v82, v225
	v_sub_f32_e32 v83, v83, v225
	v_sub_f32_e32 v84, v84, v225
	v_sub_f32_e32 v85, v85, v225
	v_sub_f32_e32 v86, v86, v225
	v_sub_f32_e32 v87, v87, v225
	v_sub_f32_e32 v88, v88, v225
	v_sub_f32_e32 v89, v89, v225
	v_sub_f32_e32 v90, v90, v225
	v_sub_f32_e32 v91, v91, v225
	v_sub_f32_e32 v92, v92, v225
	v_sub_f32_e32 v93, v93, v225
	v_sub_f32_e32 v94, v94, v225
	v_sub_f32_e32 v95, v95, v225
	v_sub_f32_e32 v64, v64, v225
	v_sub_f32_e32 v65, v65, v225
	v_sub_f32_e32 v66, v66, v225
	v_sub_f32_e32 v67, v67, v225
	v_sub_f32_e32 v68, v68, v225
	v_sub_f32_e32 v69, v69, v225
	v_sub_f32_e32 v70, v70, v225
	v_sub_f32_e32 v71, v71, v225
	v_sub_f32_e32 v72, v72, v225
	v_sub_f32_e32 v73, v73, v225
	v_sub_f32_e32 v74, v74, v225
	v_sub_f32_e32 v75, v75, v225
	v_sub_f32_e32 v76, v76, v225
	v_sub_f32_e32 v77, v77, v225
	v_sub_f32_e32 v78, v78, v225
	v_sub_f32_e32 v79, v79, v225
	v_sub_f32_e32 v48, v48, v225
	v_sub_f32_e32 v49, v49, v225
	v_sub_f32_e32 v50, v50, v225
	v_sub_f32_e32 v51, v51, v225
	v_sub_f32_e32 v52, v52, v225
	v_sub_f32_e32 v53, v53, v225
	v_sub_f32_e32 v54, v54, v225
	v_sub_f32_e32 v55, v55, v225
	v_sub_f32_e32 v56, v56, v225
	v_sub_f32_e32 v57, v57, v225
	v_sub_f32_e32 v58, v58, v225
	v_sub_f32_e32 v59, v59, v225
	v_sub_f32_e32 v60, v60, v225
	v_sub_f32_e32 v61, v61, v225
	v_sub_f32_e32 v62, v62, v225
	v_sub_f32_e32 v63, v63, v225
	v_sub_f32_e32 v32, v32, v225
	v_sub_f32_e32 v33, v33, v225
	v_sub_f32_e32 v34, v34, v225
	v_sub_f32_e32 v35, v35, v225
	v_sub_f32_e32 v36, v36, v225
	v_sub_f32_e32 v37, v37, v225
	v_sub_f32_e32 v38, v38, v225
	v_sub_f32_e32 v39, v39, v225
	v_sub_f32_e32 v40, v40, v225
	v_sub_f32_e32 v41, v41, v225
	v_sub_f32_e32 v42, v42, v225
	v_sub_f32_e32 v43, v43, v225
	v_sub_f32_e32 v44, v44, v225
	v_sub_f32_e32 v45, v45, v225
	v_sub_f32_e32 v46, v46, v225
	v_sub_f32_e32 v47, v47, v225
	v_pk_mul_f32 v[0:1], v[0:1], v[226:227] op_sel_hi:[1,0]
	v_pk_mul_f32 v[2:3], v[2:3], v[226:227] op_sel_hi:[1,0]
	v_pk_mul_f32 v[4:5], v[4:5], v[226:227] op_sel_hi:[1,0]
	v_pk_mul_f32 v[6:7], v[6:7], v[226:227] op_sel_hi:[1,0]
	v_pk_mul_f32 v[8:9], v[8:9], v[226:227] op_sel_hi:[1,0]
	v_pk_mul_f32 v[10:11], v[10:11], v[226:227] op_sel_hi:[1,0]
	v_pk_mul_f32 v[12:13], v[12:13], v[226:227] op_sel_hi:[1,0]
	v_pk_mul_f32 v[14:15], v[14:15], v[226:227] op_sel_hi:[1,0]
	v_pk_mul_f32 v[16:17], v[16:17], v[226:227] op_sel_hi:[1,0]
	v_pk_mul_f32 v[18:19], v[18:19], v[226:227] op_sel_hi:[1,0]
	v_pk_mul_f32 v[20:21], v[20:21], v[226:227] op_sel_hi:[1,0]
	v_pk_mul_f32 v[22:23], v[22:23], v[226:227] op_sel_hi:[1,0]
	v_pk_mul_f32 v[24:25], v[24:25], v[226:227] op_sel_hi:[1,0]
	v_pk_mul_f32 v[26:27], v[26:27], v[226:227] op_sel_hi:[1,0]
	v_pk_mul_f32 v[28:29], v[28:29], v[226:227] op_sel_hi:[1,0]
	v_pk_mul_f32 v[30:31], v[30:31], v[226:227] op_sel_hi:[1,0]
	v_xor_b32_e32 v228, 0x80000000, v96
	v_mov_b32_e32 v229, v228
	v_mov_b32_e32 v230, v228
	v_mov_b32_e32 v231, v228
	v_mov_b32_e32 v232, v228
	v_mov_b32_e32 v233, v228
	v_mov_b32_e32 v234, v228
	v_mov_b32_e32 v235, v228
	v_mov_b32_e32 v236, v228
	v_mov_b32_e32 v237, v228
	v_mov_b32_e32 v238, v228
	v_mov_b32_e32 v239, v228
	v_mov_b32_e32 v240, v228
	v_mov_b32_e32 v241, v228
	v_mov_b32_e32 v242, v228
	v_mov_b32_e32 v243, v228
.Lattn_o_norare:
	s_waitcnt lgkmcnt(5)
	v_mfma_f32_32x32x16_bf16 v[48:63], v[188:191], v[108:111], v[48:63]
	ds_read_b128 v[188:191], v227 offset:128
	v_exp_f32_e32 v80, v80
	v_exp_f32_e32 v81, v81
	v_exp_f32_e32 v82, v82
	v_exp_f32_e32 v83, v83
	s_waitcnt lgkmcnt(5)
	v_mfma_f32_32x32x16_bf16 v[32:47], v[192:195], v[108:111], v[32:47]
	v_exp_f32_e32 v84, v84
	v_exp_f32_e32 v85, v85
	v_exp_f32_e32 v86, v86
	v_exp_f32_e32 v87, v87
	s_waitcnt lgkmcnt(4)
	v_mfma_f32_32x32x16_bf16 v[48:63], v[196:199], v[112:115], v[48:63]
	ds_read2_b64 v[212:215], v246 offset0:4 offset1:6
	ds_read2_b64 v[216:219], v247 offset0:4 offset1:6
	v_cvt_pk_bf16_f32 v220, v80, v81
	v_cvt_pk_bf16_f32 v221, v82, v83
	v_cvt_pk_bf16_f32 v222, v84, v85
	v_cvt_pk_bf16_f32 v223, v86, v87
	v_add_f32_e32 v161, v161, v80
	v_add_f32_e32 v161, v161, v81
	v_add_f32_e32 v161, v161, v82
	v_add_f32_e32 v161, v161, v83
	s_waitcnt lgkmcnt(5)
	v_mfma_f32_32x32x16_bf16 v[0:15], v[204:207], v[220:223], v[0:15]
	v_add_f32_e32 v161, v161, v84
	v_add_f32_e32 v161, v161, v85
	v_add_f32_e32 v161, v161, v86
	v_add_f32_e32 v161, v161, v87
	v_exp_f32_e32 v88, v88
	v_exp_f32_e32 v89, v89
	s_waitcnt lgkmcnt(4)
	v_mfma_f32_32x32x16_bf16 v[16:31], v[208:211], v[220:223], v[16:31]
	ds_read_b128 v[192:195], v245 offset:128
	v_exp_f32_e32 v90, v90
	v_exp_f32_e32 v91, v91
	v_exp_f32_e32 v92, v92
	v_exp_f32_e32 v93, v93
	s_waitcnt lgkmcnt(4)
	v_mfma_f32_32x32x16_bf16 v[32:47], v[200:203], v[112:115], v[32:47]
	ds_read_b128 v[196:199], v227 offset:160
	v_exp_f32_e32 v94, v94
	v_exp_f32_e32 v95, v95
	v_cvt_pk_bf16_f32 v220, v88, v89
	v_cvt_pk_bf16_f32 v221, v90, v91
	v_cvt_pk_bf16_f32 v222, v92, v93
	v_cvt_pk_bf16_f32 v223, v94, v95
	s_waitcnt lgkmcnt(4)
	v_mfma_f32_32x32x16_bf16 v[48:63], v[188:191], v[116:119], v[48:63]
	ds_read2_b64 v[204:207], v246 offset0:8 offset1:10
	ds_read2_b64 v[208:211], v247 offset0:8 offset1:10
	v_add_f32_e32 v161, v161, v88
	v_add_f32_e32 v161, v161, v89
	v_add_f32_e32 v161, v161, v90
	v_add_f32_e32 v161, v161, v91
	v_add_f32_e32 v161, v161, v92
	v_add_f32_e32 v161, v161, v93
	v_add_f32_e32 v161, v161, v94
	v_add_f32_e32 v161, v161, v95
	s_waitcnt lgkmcnt(5)
	v_mfma_f32_32x32x16_bf16 v[0:15], v[212:215], v[220:223], v[0:15]
	v_exp_f32_e32 v64, v64
	v_exp_f32_e32 v65, v65
	v_exp_f32_e32 v66, v66
	v_exp_f32_e32 v67, v67
	s_waitcnt lgkmcnt(4)
	v_mfma_f32_32x32x16_bf16 v[16:31], v[216:219], v[220:223], v[16:31]
	ds_read_b128 v[200:203], v245 offset:160
	s_waitcnt vmcnt(0)
	ds_write_b128 v159, v[128:131]
	v_add_u32_e32 v159, s46, v169
	ds_write_b128 v159, v[124:127] offset:128
	v_add_u32_e32 v159, s46, v170
	ds_write2_b64 v159, v[132:133], v[134:135] offset1:1
	v_exp_f32_e32 v68, v68
	v_exp_f32_e32 v69, v69
	v_exp_f32_e32 v70, v70
	v_exp_f32_e32 v71, v71
	s_waitcnt lgkmcnt(7)
	v_mfma_f32_32x32x16_bf16 v[32:47], v[192:195], v[116:119], v[32:47]
	ds_read2_b64 v[212:215], v246 offset0:12 offset1:14
	ds_read2_b64 v[216:219], v247 offset0:12 offset1:14
	s_cmpk_gt_u32 s4, 0x3f
	s_cbranch_scc1 .Lattn_o_nopf
	s_add_u32 s48, s48, 0x2000
	s_addc_u32 s49, s49, 0
	s_add_u32 s50, s50, 0x1000
	s_addc_u32 s51, s51, 0
	s_add_u32 s60, s60, 0x80
	s_addc_u32 s61, s61, 0
	global_load_dwordx4 v[128:131], v154, s[48:49]
	global_load_dwordx4 v[124:127], v99, s[50:51]
	global_load_dwordx4 v[132:135], v146, s[60:61]
.Lattn_o_nopf:
	v_cvt_pk_bf16_f32 v220, v64, v65
	v_cvt_pk_bf16_f32 v221, v66, v67
	v_cvt_pk_bf16_f32 v222, v68, v69
	v_cvt_pk_bf16_f32 v223, v70, v71
	v_add_f32_e32 v161, v161, v64
	v_add_f32_e32 v161, v161, v65
	v_add_f32_e32 v161, v161, v66
	v_add_f32_e32 v161, v161, v67
	s_waitcnt lgkmcnt(8)
	v_mfma_f32_32x32x16_bf16 v[48:63], v[196:199], v[120:123], v[48:63]
	v_add_f32_e32 v161, v161, v68
	v_add_f32_e32 v161, v161, v69
	v_add_f32_e32 v161, v161, v70
	v_add_f32_e32 v161, v161, v71
	v_exp_f32_e32 v72, v72
	v_exp_f32_e32 v73, v73
	s_waitcnt lgkmcnt(7)
	v_mfma_f32_32x32x16_bf16 v[0:15], v[204:207], v[220:223], v[0:15]
	v_exp_f32_e32 v74, v74
	v_exp_f32_e32 v75, v75
	v_exp_f32_e32 v76, v76
	v_exp_f32_e32 v77, v77
	s_waitcnt lgkmcnt(6)
	v_mfma_f32_32x32x16_bf16 v[16:31], v[208:211], v[220:223], v[16:31]
	v_exp_f32_e32 v78, v78
	v_exp_f32_e32 v79, v79
	v_cvt_pk_bf16_f32 v220, v72, v73
	v_cvt_pk_bf16_f32 v221, v74, v75
	v_cvt_pk_bf16_f32 v222, v76, v77
	v_cvt_pk_bf16_f32 v223, v78, v79
	s_waitcnt lgkmcnt(5)
	v_mfma_f32_32x32x16_bf16 v[32:47], v[200:203], v[120:123], v[32:47]
	v_add_f32_e32 v161, v161, v72
	v_add_f32_e32 v161, v161, v73
	v_add_f32_e32 v161, v161, v74
	v_add_f32_e32 v161, v161, v75
	v_add_f32_e32 v161, v161, v76
	v_add_f32_e32 v161, v161, v77
	v_add_f32_e32 v161, v161, v78
	v_add_f32_e32 v161, v161, v79
	s_mov_b32 s47, s44
	s_mov_b32 s44, s45
	s_mov_b32 s45, s46
	s_mov_b32 s46, s47
	v_add_f32_e32 v157, v157, v161
	s_waitcnt lgkmcnt(0)
	s_barrier
	s_add_i32 s4, s4, 2
	s_cmpk_lt_u32 s4, 0x44
	s_cbranch_scc1 .LBB0_740
	v_mfma_f32_32x32x16_bf16 v[0:15], v[212:215], v[220:223], v[0:15]
	v_mfma_f32_32x32x16_bf16 v[16:31], v[216:219], v[220:223], v[16:31]
	s_nop 7
	s_branch .LBB0_730

	.amdhsa_kernel _Z6mk_fwd4Args
		.amdhsa_group_segment_fixed_size 0
		.amdhsa_private_segment_fixed_size 0
		.amdhsa_kernarg_size 480
		.amdhsa_user_sgpr_count 2
		.amdhsa_user_sgpr_dispatch_ptr 0
		.amdhsa_user_sgpr_queue_ptr 0
		.amdhsa_user_sgpr_kernarg_segment_ptr 1
		.amdhsa_user_sgpr_dispatch_id 0
		.amdhsa_user_sgpr_kernarg_preload_length 0
		.amdhsa_user_sgpr_kernarg_preload_offset 0
		.amdhsa_user_sgpr_private_segment_size 0
		.amdhsa_uses_dynamic_stack 0
		.amdhsa_enable_private_segment 0
		.amdhsa_system_sgpr_workgroup_id_x 1
		.amdhsa_system_sgpr_workgroup_id_y 0
		.amdhsa_system_sgpr_workgroup_id_z 0
		.amdhsa_system_sgpr_workgroup_info 0
		.amdhsa_system_vgpr_workitem_id 2
		.amdhsa_next_free_vgpr 248
		.amdhsa_next_free_sgpr 98
		.amdhsa_accum_offset 248
		.amdhsa_reserve_vcc 1
		.amdhsa_float_round_mode_32 0
		.amdhsa_float_round_mode_16_64 0
		.amdhsa_float_denorm_mode_32 3
		.amdhsa_float_denorm_mode_16_64 3
		.amdhsa_dx10_clamp 1
		.amdhsa_ieee_mode 1
		.amdhsa_fp16_overflow 0
		.amdhsa_tg_split 0
		.amdhsa_exception_fp_ieee_invalid_op 0
		.amdhsa_exception_fp_denorm_src 0
		.amdhsa_exception_fp_ieee_div_zero 0
		.amdhsa_exception_fp_ieee_overflow 0
		.amdhsa_exception_fp_ieee_underflow 0
		.amdhsa_exception_fp_ieee_inexact 0
		.amdhsa_exception_int_div_zero 0
	.end_amdhsa_kernel

amdhsa.kernels:
  - .agpr_count:     0
    .args:
      - .offset:         0
        .size:           224
        .value_kind:     by_value
      - .offset:         224
        .size:           4
        .value_kind:     hidden_block_count_x
      - .offset:         228
        .size:           4
        .value_kind:     hidden_block_count_y
      - .offset:         232
        .size:           4
        .value_kind:     hidden_block_count_z
      - .offset:         236
        .size:           2
        .value_kind:     hidden_group_size_x
      - .offset:         238
        .size:           2
        .value_kind:     hidden_group_size_y
      - .offset:         240
        .size:           2
        .value_kind:     hidden_group_size_z
      - .offset:         242
        .size:           2
        .value_kind:     hidden_remainder_x
      - .offset:         244
        .size:           2
        .value_kind:     hidden_remainder_y
      - .offset:         246
        .size:           2
        .value_kind:     hidden_remainder_z
      - .offset:         264
        .size:           8
        .value_kind:     hidden_global_offset_x
      - .offset:         272
        .size:           8
        .value_kind:     hidden_global_offset_y
      - .offset:         280
        .size:           8
        .value_kind:     hidden_global_offset_z
      - .offset:         288
        .size:           2
        .value_kind:     hidden_grid_dims
      - .offset:         312
        .size:           8
        .value_kind:     hidden_multigrid_sync_arg
      - .offset:         344
        .size:           4
        .value_kind:     hidden_dynamic_lds_size
    .group_segment_fixed_size: 0
    .kernarg_segment_align: 8
    .kernarg_segment_size: 480
    .language:       OpenCL C
    .language_version:
      - 2
      - 0
    .max_flat_workgroup_size: 512
    .name:           _Z6mk_fwd4Args
    .private_segment_fixed_size: 0
    .sgpr_count:     104
    .sgpr_spill_count: 30
    .symbol:         _Z6mk_fwd4Args.kd
    .uniform_work_group_size: 1
    .uses_dynamic_stack: false
    .vgpr_count:     248
    .vgpr_spill_count: 0
    .wavefront_size: 64
